# v28 + M7 gate-code loads and M3 gate-bias loads issued before the epilogue-alignment barrier (leading half's barrier wait hides part of their latency)
# baseline (speedup 1.0000x reference)
; __device__ __forceinline__ float sigmoidf_fast(float x) { return __builtin_amdgcn_rcpf(1.0f + __builtin_amdgcn_exp2f(-1.44269504089f * x)); }
; #define PG8_BAR __builtin_amdgcn_s_barrier()
;     __device__ __forceinline__ void operator()(const f32x4 (&acc)[2][2][4][2], const Unit& u, int wr, int wc, int fr, int fq) const {
;         const int row0 = u.pm * BM + wr * 64 + fr, colt = wc * 32 + 8 * fq, ch = u.pn * HALF + colt;
;         float b[2][8];
; #pragma unroll
;         for (int k = 0; k < 8; ++k) { b[0][k] = ba[ch + k]; b[1][k] = bx[ch + k]; }
; #pragma unroll
;         for (int ai = 0; ai < 2; ++ai)
; #pragma unroll
;             for (int m = 0; m < 4; ++m) { unsigned char* rowp = Q + (size_t)(row0 + ai * HALF + m * 16) * 2048 + u.pn * BM + colt;
; #pragma unroll
;                 for (int bj = 0; bj < 2; ++bj) { const f32x4 v0 = acc[ai][bj][m][0], v1 = acc[ai][bj][m][1]; unsigned q[8];
; #pragma unroll
;                     for (int j = 0; j < 4; ++j) { q[j] = (unsigned)(255.0f * sigmoidf_fast(v0[j] + b[bj][j]) + 0.5f); q[4 + j] = (unsigned)(255.0f * sigmoidf_fast(v1[j] + b[bj][4 + j]) + 0.5f); }
;                     u32x2 w; w.x = q[0] | (q[1] << 8) | (q[2] << 16) | (q[3] << 24); w.y = q[4] | (q[5] << 8) | (q[6] << 16) | (q[7] << 24);
;                     *(u32x2*)(rowp + bj * HALF) = w; } }
;     ...
;         if constexpr (ALIGN_EPI) { if (wr == 0) PG8_BAR; }
;         if constexpr (Q8 == 1) asm volatile("s_nop 15\n\ts_nop 15" ::: "memory");
;         if constexpr (!Epi::AFTER_DRAIN) { E(acc, cur, wr, wc, fr, fq); S.done(cur); }
.LBB0_1505:
.LBB0_1507:
	v_lshl_or_b32 v108, s67, 7, v154
	v_ashrrev_i32_e32 v109, 31, v108
	v_lshlrev_b64 v[108:109], 2, v[108:109]
	v_lshl_add_u64 v[110:111], s[42:43], 0, v[108:109]
	global_load_dwordx4 v[128:131], v[110:111], off
	global_load_dwordx4 v[124:127], v[110:111], off offset:16
	v_lshl_add_u64 v[108:109], s[44:45], 0, v[108:109]
	global_load_dwordx4 v[112:115], v[108:109], off
	s_nop 0
	global_load_dwordx4 v[108:111], v[108:109], off offset:16
	v_lshl_add_u32 v162, s56, 8, v186
	v_ashrrev_i32_e32 v163, 31, v162
	v_lshlrev_b64 v[160:161], 11, v[162:163]
	s_lshl_b32 s40, s67, 8
	s_ashr_i32 s41, s40, 31
	v_lshl_add_u64 v[160:161], s[26:27], 0, v[160:161]
	v_lshl_add_u64 v[160:161], v[160:161], 0, s[40:41]
	v_lshl_add_u64 v[160:161], v[160:161], 0, v[154:155]
	s_mov_b64 vcc, s[48:49]
	s_cbranch_vccz .Lm3_nobar
	s_barrier
.Lm3_nobar:
	s_waitcnt vmcnt(0)
	s_mov_b32 s98, 0xbfb8aa3b
	s_mov_b32 s99, 0xbfb8aa3b
	v_pk_add_f32 v[190:191], v[144:145], v[128:129]
	v_pk_add_f32 v[192:193], v[146:147], v[130:131]
	v_pk_add_f32 v[194:195], v[140:141], v[124:125]
	v_pk_add_f32 v[196:197], v[142:143], v[126:127]
	v_pk_mul_f32 v[190:191], v[190:191], s[98:99]
	v_pk_mul_f32 v[192:193], v[192:193], s[98:99]
	v_pk_mul_f32 v[194:195], v[194:195], s[98:99]
	v_pk_mul_f32 v[196:197], v[196:197], s[98:99]
	v_exp_f32_e32 v190, v190
	v_exp_f32_e32 v191, v191
	v_exp_f32_e32 v192, v192
	v_exp_f32_e32 v193, v193
	v_exp_f32_e32 v194, v194
	v_exp_f32_e32 v195, v195
	v_exp_f32_e32 v196, v196
	v_exp_f32_e32 v197, v197
	v_pk_add_f32 v[190:191], v[190:191], 1.0 op_sel_hi:[1,0]
	v_pk_add_f32 v[192:193], v[192:193], 1.0 op_sel_hi:[1,0]
	v_pk_add_f32 v[194:195], v[194:195], 1.0 op_sel_hi:[1,0]
	v_pk_add_f32 v[196:197], v[196:197], 1.0 op_sel_hi:[1,0]
	v_rcp_f32_e32 v190, v190
	v_rcp_f32_e32 v191, v191
	v_rcp_f32_e32 v192, v192
	v_rcp_f32_e32 v193, v193
	v_rcp_f32_e32 v194, v194
	v_rcp_f32_e32 v195, v195
	v_rcp_f32_e32 v196, v196
	v_rcp_f32_e32 v197, v197
	v_pk_fma_f32 v[190:191], v[190:191], s[2:3], 0.5 op_sel_hi:[1,0,0]
	v_pk_fma_f32 v[192:193], v[192:193], s[2:3], 0.5 op_sel_hi:[1,0,0]
	v_pk_fma_f32 v[194:195], v[194:195], s[2:3], 0.5 op_sel_hi:[1,0,0]
	v_pk_fma_f32 v[196:197], v[196:197], s[2:3], 0.5 op_sel_hi:[1,0,0]
	v_cvt_u32_f32_e32 v190, v190
	v_cvt_u32_f32_e32 v191, v191
	v_cvt_u32_f32_sdwa v192, v192 dst_sel:WORD_1 dst_unused:UNUSED_PAD src0_sel:DWORD
	v_cvt_u32_f32_sdwa v193, v193 dst_sel:BYTE_3 dst_unused:UNUSED_PAD src0_sel:DWORD
	v_cvt_u32_f32_e32 v194, v194
	v_cvt_u32_f32_e32 v195, v195
	v_cvt_u32_f32_sdwa v196, v196 dst_sel:WORD_1 dst_unused:UNUSED_PAD src0_sel:DWORD
	v_cvt_u32_f32_sdwa v197, v197 dst_sel:BYTE_3 dst_unused:UNUSED_PAD src0_sel:DWORD
	v_lshl_or_b32 v190, v191, 8, v190
	v_lshl_or_b32 v194, v195, 8, v194
	v_or3_b32 v190, v190, v192, v193
	v_or3_b32 v191, v194, v196, v197
	global_store_dwordx2 v[160:161], v[190:191], off
	v_pk_add_f32 v[198:199], v[136:137], v[112:113]
	v_pk_add_f32 v[200:201], v[138:139], v[114:115]
	v_pk_add_f32 v[202:203], v[132:133], v[108:109]
	v_pk_add_f32 v[204:205], v[134:135], v[110:111]
	v_pk_mul_f32 v[198:199], v[198:199], s[98:99]
	v_pk_mul_f32 v[200:201], v[200:201], s[98:99]
	v_pk_mul_f32 v[202:203], v[202:203], s[98:99]
	v_pk_mul_f32 v[204:205], v[204:205], s[98:99]
	v_exp_f32_e32 v198, v198
	v_exp_f32_e32 v199, v199
	v_exp_f32_e32 v200, v200
	v_exp_f32_e32 v201, v201
	v_exp_f32_e32 v202, v202
	v_exp_f32_e32 v203, v203
	v_exp_f32_e32 v204, v204
	v_exp_f32_e32 v205, v205
	v_pk_add_f32 v[198:199], v[198:199], 1.0 op_sel_hi:[1,0]
	v_pk_add_f32 v[200:201], v[200:201], 1.0 op_sel_hi:[1,0]
	v_pk_add_f32 v[202:203], v[202:203], 1.0 op_sel_hi:[1,0]
	v_pk_add_f32 v[204:205], v[204:205], 1.0 op_sel_hi:[1,0]
	v_rcp_f32_e32 v198, v198
	v_rcp_f32_e32 v199, v199
	v_rcp_f32_e32 v200, v200
	v_rcp_f32_e32 v201, v201
	v_rcp_f32_e32 v202, v202
	v_rcp_f32_e32 v203, v203
	v_rcp_f32_e32 v204, v204
	v_rcp_f32_e32 v205, v205
	v_pk_fma_f32 v[198:199], v[198:199], s[2:3], 0.5 op_sel_hi:[1,0,0]
	v_pk_fma_f32 v[200:201], v[200:201], s[2:3], 0.5 op_sel_hi:[1,0,0]
	v_pk_fma_f32 v[202:203], v[202:203], s[2:3], 0.5 op_sel_hi:[1,0,0]
	v_pk_fma_f32 v[204:205], v[204:205], s[2:3], 0.5 op_sel_hi:[1,0,0]
	v_cvt_u32_f32_e32 v198, v198
	v_cvt_u32_f32_e32 v199, v199
	v_cvt_u32_f32_sdwa v200, v200 dst_sel:WORD_1 dst_unused:UNUSED_PAD src0_sel:DWORD
	v_cvt_u32_f32_sdwa v201, v201 dst_sel:BYTE_3 dst_unused:UNUSED_PAD src0_sel:DWORD
	v_cvt_u32_f32_e32 v202, v202
	v_cvt_u32_f32_e32 v203, v203
	v_cvt_u32_f32_sdwa v204, v204 dst_sel:WORD_1 dst_unused:UNUSED_PAD src0_sel:DWORD
	v_cvt_u32_f32_sdwa v205, v205 dst_sel:BYTE_3 dst_unused:UNUSED_PAD src0_sel:DWORD
	v_lshl_or_b32 v198, v199, 8, v198
	v_lshl_or_b32 v202, v203, 8, v202
	v_or3_b32 v198, v198, v200, v201
	v_or3_b32 v199, v202, v204, v205
	global_store_dwordx2 v[160:161], v[198:199], off offset:128
	v_pk_add_f32 v[190:191], v[120:121], v[128:129]
	v_pk_add_f32 v[192:193], v[122:123], v[130:131]
	v_pk_add_f32 v[194:195], v[116:117], v[124:125]
	v_pk_add_f32 v[196:197], v[118:119], v[126:127]
	v_pk_mul_f32 v[190:191], v[190:191], s[98:99]
	v_pk_mul_f32 v[192:193], v[192:193], s[98:99]
	v_pk_mul_f32 v[194:195], v[194:195], s[98:99]
	v_pk_mul_f32 v[196:197], v[196:197], s[98:99]
	v_exp_f32_e32 v190, v190
	v_exp_f32_e32 v191, v191
	v_exp_f32_e32 v192, v192
	v_exp_f32_e32 v193, v193
	v_exp_f32_e32 v194, v194
	v_exp_f32_e32 v195, v195
	v_exp_f32_e32 v196, v196
	v_exp_f32_e32 v197, v197
	v_pk_add_f32 v[190:191], v[190:191], 1.0 op_sel_hi:[1,0]
	v_pk_add_f32 v[192:193], v[192:193], 1.0 op_sel_hi:[1,0]
	v_pk_add_f32 v[194:195], v[194:195], 1.0 op_sel_hi:[1,0]
	v_pk_add_f32 v[196:197], v[196:197], 1.0 op_sel_hi:[1,0]
; __device__ __forceinline__ float sigmoidf_fast(float x) { return __builtin_amdgcn_rcpf(1.0f + __builtin_amdgcn_exp2f(-1.44269504089f * x)); }
;     __device__ __forceinline__ void operator()(const f32x4 (&acc)[2][2][4][2], const Unit& u, int wr, int wc, int fr, int fq) const {
;     ...
;                 for (int bj = 0; bj < 2; ++bj) { const f32x4 v0 = acc[ai][bj][m][0], v1 = acc[ai][bj][m][1]; unsigned q[8];
; #pragma unroll
;                     for (int j = 0; j < 4; ++j) { q[j] = (unsigned)(255.0f * sigmoidf_fast(v0[j] + b[bj][j]) + 0.5f); q[4 + j] = (unsigned)(255.0f * sigmoidf_fast(v1[j] + b[bj][4 + j]) + 0.5f); }
;                     u32x2 w; w.x = q[0] | (q[1] << 8) | (q[2] << 16) | (q[3] << 24); w.y = q[4] | (q[5] << 8) | (q[6] << 16) | (q[7] << 24);
;                     *(u32x2*)(rowp + bj * HALF) = w; } }
	v_rcp_f32_e32 v190, v190
	v_rcp_f32_e32 v191, v191
	v_rcp_f32_e32 v192, v192
	v_rcp_f32_e32 v193, v193
	v_rcp_f32_e32 v194, v194
	v_rcp_f32_e32 v195, v195
	v_rcp_f32_e32 v196, v196
	v_rcp_f32_e32 v197, v197
	v_pk_fma_f32 v[190:191], v[190:191], s[2:3], 0.5 op_sel_hi:[1,0,0]
	v_pk_fma_f32 v[192:193], v[192:193], s[2:3], 0.5 op_sel_hi:[1,0,0]
	v_pk_fma_f32 v[194:195], v[194:195], s[2:3], 0.5 op_sel_hi:[1,0,0]
	v_pk_fma_f32 v[196:197], v[196:197], s[2:3], 0.5 op_sel_hi:[1,0,0]
	v_cvt_u32_f32_e32 v190, v190
	v_cvt_u32_f32_e32 v191, v191
	v_cvt_u32_f32_sdwa v192, v192 dst_sel:WORD_1 dst_unused:UNUSED_PAD src0_sel:DWORD
	v_cvt_u32_f32_sdwa v193, v193 dst_sel:BYTE_3 dst_unused:UNUSED_PAD src0_sel:DWORD
	v_cvt_u32_f32_e32 v194, v194
	v_cvt_u32_f32_e32 v195, v195
	v_cvt_u32_f32_sdwa v196, v196 dst_sel:WORD_1 dst_unused:UNUSED_PAD src0_sel:DWORD
	v_cvt_u32_f32_sdwa v197, v197 dst_sel:BYTE_3 dst_unused:UNUSED_PAD src0_sel:DWORD
	s_mov_b64 s[40:41], 0x8000
	v_lshl_add_u64 v[206:207], v[160:161], 0, s[40:41]
	v_lshl_or_b32 v190, v191, 8, v190
	v_lshl_or_b32 v194, v195, 8, v194
	v_or3_b32 v190, v190, v192, v193
	v_or3_b32 v191, v194, v196, v197
	global_store_dwordx2 v[206:207], v[190:191], off
	v_pk_add_f32 v[198:199], v[104:105], v[112:113]
	v_pk_add_f32 v[200:201], v[106:107], v[114:115]
	v_pk_add_f32 v[202:203], v[100:101], v[108:109]
	v_pk_add_f32 v[204:205], v[102:103], v[110:111]
	v_pk_mul_f32 v[198:199], v[198:199], s[98:99]
	v_pk_mul_f32 v[200:201], v[200:201], s[98:99]
	v_pk_mul_f32 v[202:203], v[202:203], s[98:99]
	v_pk_mul_f32 v[204:205], v[204:205], s[98:99]
	v_exp_f32_e32 v198, v198
	v_exp_f32_e32 v199, v199
	v_exp_f32_e32 v200, v200
	v_exp_f32_e32 v201, v201
	v_exp_f32_e32 v202, v202
	v_exp_f32_e32 v203, v203
	v_exp_f32_e32 v204, v204
	v_exp_f32_e32 v205, v205
	v_pk_add_f32 v[198:199], v[198:199], 1.0 op_sel_hi:[1,0]
	v_pk_add_f32 v[200:201], v[200:201], 1.0 op_sel_hi:[1,0]
	v_pk_add_f32 v[202:203], v[202:203], 1.0 op_sel_hi:[1,0]
	v_pk_add_f32 v[204:205], v[204:205], 1.0 op_sel_hi:[1,0]
	v_rcp_f32_e32 v198, v198
	v_rcp_f32_e32 v199, v199
	v_rcp_f32_e32 v200, v200
	v_rcp_f32_e32 v201, v201
	v_rcp_f32_e32 v202, v202
	v_rcp_f32_e32 v203, v203
	v_rcp_f32_e32 v204, v204
	v_rcp_f32_e32 v205, v205
	v_pk_fma_f32 v[198:199], v[198:199], s[2:3], 0.5 op_sel_hi:[1,0,0]
	v_pk_fma_f32 v[200:201], v[200:201], s[2:3], 0.5 op_sel_hi:[1,0,0]
	v_pk_fma_f32 v[202:203], v[202:203], s[2:3], 0.5 op_sel_hi:[1,0,0]
	v_pk_fma_f32 v[204:205], v[204:205], s[2:3], 0.5 op_sel_hi:[1,0,0]
	v_cvt_u32_f32_e32 v198, v198
	v_cvt_u32_f32_e32 v199, v199
	v_cvt_u32_f32_sdwa v200, v200 dst_sel:WORD_1 dst_unused:UNUSED_PAD src0_sel:DWORD
	v_cvt_u32_f32_sdwa v201, v201 dst_sel:BYTE_3 dst_unused:UNUSED_PAD src0_sel:DWORD
	v_cvt_u32_f32_e32 v202, v202
	v_cvt_u32_f32_e32 v203, v203
	v_cvt_u32_f32_sdwa v204, v204 dst_sel:WORD_1 dst_unused:UNUSED_PAD src0_sel:DWORD
	v_cvt_u32_f32_sdwa v205, v205 dst_sel:BYTE_3 dst_unused:UNUSED_PAD src0_sel:DWORD
	v_lshl_or_b32 v198, v199, 8, v198
	v_lshl_or_b32 v202, v203, 8, v202
	v_or3_b32 v198, v198, v200, v201
	v_or3_b32 v199, v202, v204, v205
	global_store_dwordx2 v[206:207], v[198:199], off offset:128
	v_pk_add_f32 v[190:191], v[96:97], v[128:129]
	v_pk_add_f32 v[192:193], v[98:99], v[130:131]
	v_pk_add_f32 v[194:195], v[92:93], v[124:125]
	v_pk_add_f32 v[196:197], v[94:95], v[126:127]
	v_pk_mul_f32 v[190:191], v[190:191], s[98:99]
	v_pk_mul_f32 v[192:193], v[192:193], s[98:99]
	v_pk_mul_f32 v[194:195], v[194:195], s[98:99]
	v_pk_mul_f32 v[196:197], v[196:197], s[98:99]
	v_exp_f32_e32 v190, v190
	v_exp_f32_e32 v191, v191
	v_exp_f32_e32 v192, v192
	v_exp_f32_e32 v193, v193
	v_exp_f32_e32 v194, v194
	v_exp_f32_e32 v195, v195
	v_exp_f32_e32 v196, v196
	v_exp_f32_e32 v197, v197
	v_pk_add_f32 v[190:191], v[190:191], 1.0 op_sel_hi:[1,0]
	v_pk_add_f32 v[192:193], v[192:193], 1.0 op_sel_hi:[1,0]
	v_pk_add_f32 v[194:195], v[194:195], 1.0 op_sel_hi:[1,0]
	v_pk_add_f32 v[196:197], v[196:197], 1.0 op_sel_hi:[1,0]
	v_rcp_f32_e32 v190, v190
	v_rcp_f32_e32 v191, v191
	v_rcp_f32_e32 v192, v192
	v_rcp_f32_e32 v193, v193
	v_rcp_f32_e32 v194, v194
	v_rcp_f32_e32 v195, v195
	v_rcp_f32_e32 v196, v196
	v_rcp_f32_e32 v197, v197
	v_pk_fma_f32 v[190:191], v[190:191], s[2:3], 0.5 op_sel_hi:[1,0,0]
	v_pk_fma_f32 v[192:193], v[192:193], s[2:3], 0.5 op_sel_hi:[1,0,0]
	v_pk_fma_f32 v[194:195], v[194:195], s[2:3], 0.5 op_sel_hi:[1,0,0]
	v_pk_fma_f32 v[196:197], v[196:197], s[2:3], 0.5 op_sel_hi:[1,0,0]
	v_cvt_u32_f32_e32 v190, v190
	v_cvt_u32_f32_e32 v191, v191
	v_cvt_u32_f32_sdwa v192, v192 dst_sel:WORD_1 dst_unused:UNUSED_PAD src0_sel:DWORD
	v_cvt_u32_f32_sdwa v193, v193 dst_sel:BYTE_3 dst_unused:UNUSED_PAD src0_sel:DWORD
	v_cvt_u32_f32_e32 v194, v194
	v_cvt_u32_f32_e32 v195, v195
	v_cvt_u32_f32_sdwa v196, v196 dst_sel:WORD_1 dst_unused:UNUSED_PAD src0_sel:DWORD
	v_cvt_u32_f32_sdwa v197, v197 dst_sel:BYTE_3 dst_unused:UNUSED_PAD src0_sel:DWORD
	s_mov_b64 s[40:41], 0x10000
	v_lshl_add_u64 v[208:209], v[160:161], 0, s[40:41]
	v_lshl_or_b32 v190, v191, 8, v190
	v_lshl_or_b32 v194, v195, 8, v194
	v_or3_b32 v190, v190, v192, v193
	v_or3_b32 v191, v194, v196, v197
	global_store_dwordx2 v[208:209], v[190:191], off
	v_pk_add_f32 v[198:199], v[88:89], v[112:113]
	v_pk_add_f32 v[200:201], v[90:91], v[114:115]
	v_pk_add_f32 v[202:203], v[84:85], v[108:109]
	v_pk_add_f32 v[204:205], v[86:87], v[110:111]
	v_pk_mul_f32 v[198:199], v[198:199], s[98:99]
	v_pk_mul_f32 v[200:201], v[200:201], s[98:99]
	v_pk_mul_f32 v[202:203], v[202:203], s[98:99]
	v_pk_mul_f32 v[204:205], v[204:205], s[98:99]
	v_exp_f32_e32 v198, v198
	v_exp_f32_e32 v199, v199
	v_exp_f32_e32 v200, v200
	v_exp_f32_e32 v201, v201
; __device__ __forceinline__ float sigmoidf_fast(float x) { return __builtin_amdgcn_rcpf(1.0f + __builtin_amdgcn_exp2f(-1.44269504089f * x)); }
;     __device__ __forceinline__ void operator()(const f32x4 (&acc)[2][2][4][2], const Unit& u, int wr, int wc, int fr, int fq) const {
;     ...
;                 for (int bj = 0; bj < 2; ++bj) { const f32x4 v0 = acc[ai][bj][m][0], v1 = acc[ai][bj][m][1]; unsigned q[8];
; #pragma unroll
;                     for (int j = 0; j < 4; ++j) { q[j] = (unsigned)(255.0f * sigmoidf_fast(v0[j] + b[bj][j]) + 0.5f); q[4 + j] = (unsigned)(255.0f * sigmoidf_fast(v1[j] + b[bj][4 + j]) + 0.5f); }
;                     u32x2 w; w.x = q[0] | (q[1] << 8) | (q[2] << 16) | (q[3] << 24); w.y = q[4] | (q[5] << 8) | (q[6] << 16) | (q[7] << 24);
;                     *(u32x2*)(rowp + bj * HALF) = w; } }
	v_exp_f32_e32 v202, v202
	v_exp_f32_e32 v203, v203
	v_exp_f32_e32 v204, v204
	v_exp_f32_e32 v205, v205
	v_pk_add_f32 v[198:199], v[198:199], 1.0 op_sel_hi:[1,0]
	v_pk_add_f32 v[200:201], v[200:201], 1.0 op_sel_hi:[1,0]
	v_pk_add_f32 v[202:203], v[202:203], 1.0 op_sel_hi:[1,0]
	v_pk_add_f32 v[204:205], v[204:205], 1.0 op_sel_hi:[1,0]
	v_rcp_f32_e32 v198, v198
	v_rcp_f32_e32 v199, v199
	v_rcp_f32_e32 v200, v200
	v_rcp_f32_e32 v201, v201
	v_rcp_f32_e32 v202, v202
	v_rcp_f32_e32 v203, v203
	v_rcp_f32_e32 v204, v204
	v_rcp_f32_e32 v205, v205
	v_pk_fma_f32 v[198:199], v[198:199], s[2:3], 0.5 op_sel_hi:[1,0,0]
	v_pk_fma_f32 v[200:201], v[200:201], s[2:3], 0.5 op_sel_hi:[1,0,0]
	v_pk_fma_f32 v[202:203], v[202:203], s[2:3], 0.5 op_sel_hi:[1,0,0]
	v_pk_fma_f32 v[204:205], v[204:205], s[2:3], 0.5 op_sel_hi:[1,0,0]
	v_cvt_u32_f32_e32 v198, v198
	v_cvt_u32_f32_e32 v199, v199
	v_cvt_u32_f32_sdwa v200, v200 dst_sel:WORD_1 dst_unused:UNUSED_PAD src0_sel:DWORD
	v_cvt_u32_f32_sdwa v201, v201 dst_sel:BYTE_3 dst_unused:UNUSED_PAD src0_sel:DWORD
	v_cvt_u32_f32_e32 v202, v202
	v_cvt_u32_f32_e32 v203, v203
	v_cvt_u32_f32_sdwa v204, v204 dst_sel:WORD_1 dst_unused:UNUSED_PAD src0_sel:DWORD
	v_cvt_u32_f32_sdwa v205, v205 dst_sel:BYTE_3 dst_unused:UNUSED_PAD src0_sel:DWORD
	v_lshl_or_b32 v198, v199, 8, v198
	v_lshl_or_b32 v202, v203, 8, v202
	v_or3_b32 v198, v198, v200, v201
	v_or3_b32 v199, v202, v204, v205
	global_store_dwordx2 v[208:209], v[198:199], off offset:128
	v_pk_add_f32 v[190:191], v[80:81], v[128:129]
	v_pk_add_f32 v[192:193], v[82:83], v[130:131]
	v_pk_add_f32 v[194:195], v[76:77], v[124:125]
	v_pk_add_f32 v[196:197], v[78:79], v[126:127]
	v_pk_mul_f32 v[190:191], v[190:191], s[98:99]
	v_pk_mul_f32 v[192:193], v[192:193], s[98:99]
	v_pk_mul_f32 v[194:195], v[194:195], s[98:99]
	v_pk_mul_f32 v[196:197], v[196:197], s[98:99]
	v_exp_f32_e32 v190, v190
	v_exp_f32_e32 v191, v191
	v_exp_f32_e32 v192, v192
	v_exp_f32_e32 v193, v193
	v_exp_f32_e32 v194, v194
	v_exp_f32_e32 v195, v195
	v_exp_f32_e32 v196, v196
	v_exp_f32_e32 v197, v197
	v_pk_add_f32 v[190:191], v[190:191], 1.0 op_sel_hi:[1,0]
	v_pk_add_f32 v[192:193], v[192:193], 1.0 op_sel_hi:[1,0]
	v_pk_add_f32 v[194:195], v[194:195], 1.0 op_sel_hi:[1,0]
	v_pk_add_f32 v[196:197], v[196:197], 1.0 op_sel_hi:[1,0]
	v_rcp_f32_e32 v190, v190
	v_rcp_f32_e32 v191, v191
	v_rcp_f32_e32 v192, v192
	v_rcp_f32_e32 v193, v193
	v_rcp_f32_e32 v194, v194
	v_rcp_f32_e32 v195, v195
	v_rcp_f32_e32 v196, v196
	v_rcp_f32_e32 v197, v197
	v_pk_fma_f32 v[190:191], v[190:191], s[2:3], 0.5 op_sel_hi:[1,0,0]
	v_pk_fma_f32 v[192:193], v[192:193], s[2:3], 0.5 op_sel_hi:[1,0,0]
	v_pk_fma_f32 v[194:195], v[194:195], s[2:3], 0.5 op_sel_hi:[1,0,0]
	v_pk_fma_f32 v[196:197], v[196:197], s[2:3], 0.5 op_sel_hi:[1,0,0]
	v_cvt_u32_f32_e32 v190, v190
	v_cvt_u32_f32_e32 v191, v191
	v_cvt_u32_f32_sdwa v192, v192 dst_sel:WORD_1 dst_unused:UNUSED_PAD src0_sel:DWORD
	v_cvt_u32_f32_sdwa v193, v193 dst_sel:BYTE_3 dst_unused:UNUSED_PAD src0_sel:DWORD
	v_cvt_u32_f32_e32 v194, v194
	v_cvt_u32_f32_e32 v195, v195
	v_cvt_u32_f32_sdwa v196, v196 dst_sel:WORD_1 dst_unused:UNUSED_PAD src0_sel:DWORD
	v_cvt_u32_f32_sdwa v197, v197 dst_sel:BYTE_3 dst_unused:UNUSED_PAD src0_sel:DWORD
	s_mov_b64 s[40:41], 0x18000
	v_lshl_add_u64 v[206:207], v[160:161], 0, s[40:41]
	v_lshl_or_b32 v190, v191, 8, v190
	v_lshl_or_b32 v194, v195, 8, v194
	v_or3_b32 v190, v190, v192, v193
	v_or3_b32 v191, v194, v196, v197
	global_store_dwordx2 v[206:207], v[190:191], off
	v_pk_add_f32 v[198:199], v[72:73], v[112:113]
	v_pk_add_f32 v[200:201], v[74:75], v[114:115]
	v_pk_add_f32 v[202:203], v[68:69], v[108:109]
	v_pk_add_f32 v[204:205], v[70:71], v[110:111]
	v_pk_mul_f32 v[198:199], v[198:199], s[98:99]
	v_pk_mul_f32 v[200:201], v[200:201], s[98:99]
	v_pk_mul_f32 v[202:203], v[202:203], s[98:99]
	v_pk_mul_f32 v[204:205], v[204:205], s[98:99]
	v_exp_f32_e32 v198, v198
	v_exp_f32_e32 v199, v199
	v_exp_f32_e32 v200, v200
	v_exp_f32_e32 v201, v201
	v_exp_f32_e32 v202, v202
	v_exp_f32_e32 v203, v203
	v_exp_f32_e32 v204, v204
	v_exp_f32_e32 v205, v205
	v_pk_add_f32 v[198:199], v[198:199], 1.0 op_sel_hi:[1,0]
	v_pk_add_f32 v[200:201], v[200:201], 1.0 op_sel_hi:[1,0]
	v_pk_add_f32 v[202:203], v[202:203], 1.0 op_sel_hi:[1,0]
	v_pk_add_f32 v[204:205], v[204:205], 1.0 op_sel_hi:[1,0]
	v_rcp_f32_e32 v198, v198
	v_rcp_f32_e32 v199, v199
	v_rcp_f32_e32 v200, v200
	v_rcp_f32_e32 v201, v201
	v_rcp_f32_e32 v202, v202
	v_rcp_f32_e32 v203, v203
	v_rcp_f32_e32 v204, v204
	v_rcp_f32_e32 v205, v205
	v_pk_fma_f32 v[198:199], v[198:199], s[2:3], 0.5 op_sel_hi:[1,0,0]
	v_pk_fma_f32 v[200:201], v[200:201], s[2:3], 0.5 op_sel_hi:[1,0,0]
	v_pk_fma_f32 v[202:203], v[202:203], s[2:3], 0.5 op_sel_hi:[1,0,0]
	v_pk_fma_f32 v[204:205], v[204:205], s[2:3], 0.5 op_sel_hi:[1,0,0]
	v_cvt_u32_f32_e32 v198, v198
	v_cvt_u32_f32_e32 v199, v199
	v_cvt_u32_f32_sdwa v200, v200 dst_sel:WORD_1 dst_unused:UNUSED_PAD src0_sel:DWORD
	v_cvt_u32_f32_sdwa v201, v201 dst_sel:BYTE_3 dst_unused:UNUSED_PAD src0_sel:DWORD
	v_cvt_u32_f32_e32 v202, v202
	v_cvt_u32_f32_e32 v203, v203
	v_cvt_u32_f32_sdwa v204, v204 dst_sel:WORD_1 dst_unused:UNUSED_PAD src0_sel:DWORD
	v_cvt_u32_f32_sdwa v205, v205 dst_sel:BYTE_3 dst_unused:UNUSED_PAD src0_sel:DWORD
	v_lshl_or_b32 v198, v199, 8, v198
	v_lshl_or_b32 v202, v203, 8, v202
	v_or3_b32 v198, v198, v200, v201
	v_or3_b32 v199, v202, v204, v205
	global_store_dwordx2 v[206:207], v[198:199], off offset:128
	v_pk_add_f32 v[190:191], v[64:65], v[128:129]
	v_pk_add_f32 v[192:193], v[66:67], v[130:131]
	v_pk_add_f32 v[194:195], v[60:61], v[124:125]
	v_pk_add_f32 v[196:197], v[62:63], v[126:127]
; __device__ __forceinline__ float sigmoidf_fast(float x) { return __builtin_amdgcn_rcpf(1.0f + __builtin_amdgcn_exp2f(-1.44269504089f * x)); }
;     __device__ __forceinline__ void operator()(const f32x4 (&acc)[2][2][4][2], const Unit& u, int wr, int wc, int fr, int fq) const {
;     ...
;                 for (int bj = 0; bj < 2; ++bj) { const f32x4 v0 = acc[ai][bj][m][0], v1 = acc[ai][bj][m][1]; unsigned q[8];
; #pragma unroll
;                     for (int j = 0; j < 4; ++j) { q[j] = (unsigned)(255.0f * sigmoidf_fast(v0[j] + b[bj][j]) + 0.5f); q[4 + j] = (unsigned)(255.0f * sigmoidf_fast(v1[j] + b[bj][4 + j]) + 0.5f); }
;                     u32x2 w; w.x = q[0] | (q[1] << 8) | (q[2] << 16) | (q[3] << 24); w.y = q[4] | (q[5] << 8) | (q[6] << 16) | (q[7] << 24);
;                     *(u32x2*)(rowp + bj * HALF) = w; } }
	v_pk_mul_f32 v[190:191], v[190:191], s[98:99]
	v_pk_mul_f32 v[192:193], v[192:193], s[98:99]
	v_pk_mul_f32 v[194:195], v[194:195], s[98:99]
	v_pk_mul_f32 v[196:197], v[196:197], s[98:99]
	v_exp_f32_e32 v190, v190
	v_exp_f32_e32 v191, v191
	v_exp_f32_e32 v192, v192
	v_exp_f32_e32 v193, v193
	v_exp_f32_e32 v194, v194
	v_exp_f32_e32 v195, v195
	v_exp_f32_e32 v196, v196
	v_exp_f32_e32 v197, v197
	v_pk_add_f32 v[190:191], v[190:191], 1.0 op_sel_hi:[1,0]
	v_pk_add_f32 v[192:193], v[192:193], 1.0 op_sel_hi:[1,0]
	v_pk_add_f32 v[194:195], v[194:195], 1.0 op_sel_hi:[1,0]
	v_pk_add_f32 v[196:197], v[196:197], 1.0 op_sel_hi:[1,0]
	v_rcp_f32_e32 v190, v190
	v_rcp_f32_e32 v191, v191
	v_rcp_f32_e32 v192, v192
	v_rcp_f32_e32 v193, v193
	v_rcp_f32_e32 v194, v194
	v_rcp_f32_e32 v195, v195
	v_rcp_f32_e32 v196, v196
	v_rcp_f32_e32 v197, v197
	v_pk_fma_f32 v[190:191], v[190:191], s[2:3], 0.5 op_sel_hi:[1,0,0]
	v_pk_fma_f32 v[192:193], v[192:193], s[2:3], 0.5 op_sel_hi:[1,0,0]
	v_pk_fma_f32 v[194:195], v[194:195], s[2:3], 0.5 op_sel_hi:[1,0,0]
	v_pk_fma_f32 v[196:197], v[196:197], s[2:3], 0.5 op_sel_hi:[1,0,0]
	v_cvt_u32_f32_e32 v190, v190
	v_cvt_u32_f32_e32 v191, v191
	v_cvt_u32_f32_sdwa v192, v192 dst_sel:WORD_1 dst_unused:UNUSED_PAD src0_sel:DWORD
	v_cvt_u32_f32_sdwa v193, v193 dst_sel:BYTE_3 dst_unused:UNUSED_PAD src0_sel:DWORD
	v_cvt_u32_f32_e32 v194, v194
	v_cvt_u32_f32_e32 v195, v195
	v_cvt_u32_f32_sdwa v196, v196 dst_sel:WORD_1 dst_unused:UNUSED_PAD src0_sel:DWORD
	v_cvt_u32_f32_sdwa v197, v197 dst_sel:BYTE_3 dst_unused:UNUSED_PAD src0_sel:DWORD
	s_mov_b64 s[40:41], 0x40000
	v_lshl_add_u64 v[208:209], v[160:161], 0, s[40:41]
	v_lshl_or_b32 v190, v191, 8, v190
	v_lshl_or_b32 v194, v195, 8, v194
	v_or3_b32 v190, v190, v192, v193
	v_or3_b32 v191, v194, v196, v197
	global_store_dwordx2 v[208:209], v[190:191], off
	v_pk_add_f32 v[198:199], v[56:57], v[112:113]
	v_pk_add_f32 v[200:201], v[58:59], v[114:115]
	v_pk_add_f32 v[202:203], v[52:53], v[108:109]
	v_pk_add_f32 v[204:205], v[54:55], v[110:111]
	v_pk_mul_f32 v[198:199], v[198:199], s[98:99]
	v_pk_mul_f32 v[200:201], v[200:201], s[98:99]
	v_pk_mul_f32 v[202:203], v[202:203], s[98:99]
	v_pk_mul_f32 v[204:205], v[204:205], s[98:99]
	v_exp_f32_e32 v198, v198
	v_exp_f32_e32 v199, v199
	v_exp_f32_e32 v200, v200
	v_exp_f32_e32 v201, v201
	v_exp_f32_e32 v202, v202
	v_exp_f32_e32 v203, v203
	v_exp_f32_e32 v204, v204
	v_exp_f32_e32 v205, v205
	v_pk_add_f32 v[198:199], v[198:199], 1.0 op_sel_hi:[1,0]
	v_pk_add_f32 v[200:201], v[200:201], 1.0 op_sel_hi:[1,0]
	v_pk_add_f32 v[202:203], v[202:203], 1.0 op_sel_hi:[1,0]
	v_pk_add_f32 v[204:205], v[204:205], 1.0 op_sel_hi:[1,0]
	v_rcp_f32_e32 v198, v198
	v_rcp_f32_e32 v199, v199
	v_rcp_f32_e32 v200, v200
	v_rcp_f32_e32 v201, v201
	v_rcp_f32_e32 v202, v202
	v_rcp_f32_e32 v203, v203
	v_rcp_f32_e32 v204, v204
	v_rcp_f32_e32 v205, v205
	v_pk_fma_f32 v[198:199], v[198:199], s[2:3], 0.5 op_sel_hi:[1,0,0]
	v_pk_fma_f32 v[200:201], v[200:201], s[2:3], 0.5 op_sel_hi:[1,0,0]
	v_pk_fma_f32 v[202:203], v[202:203], s[2:3], 0.5 op_sel_hi:[1,0,0]
	v_pk_fma_f32 v[204:205], v[204:205], s[2:3], 0.5 op_sel_hi:[1,0,0]
	v_cvt_u32_f32_e32 v198, v198
	v_cvt_u32_f32_e32 v199, v199
	v_cvt_u32_f32_sdwa v200, v200 dst_sel:WORD_1 dst_unused:UNUSED_PAD src0_sel:DWORD
	v_cvt_u32_f32_sdwa v201, v201 dst_sel:BYTE_3 dst_unused:UNUSED_PAD src0_sel:DWORD
	v_cvt_u32_f32_e32 v202, v202
	v_cvt_u32_f32_e32 v203, v203
	v_cvt_u32_f32_sdwa v204, v204 dst_sel:WORD_1 dst_unused:UNUSED_PAD src0_sel:DWORD
	v_cvt_u32_f32_sdwa v205, v205 dst_sel:BYTE_3 dst_unused:UNUSED_PAD src0_sel:DWORD
	v_lshl_or_b32 v198, v199, 8, v198
	v_lshl_or_b32 v202, v203, 8, v202
	v_or3_b32 v198, v198, v200, v201
	v_or3_b32 v199, v202, v204, v205
	global_store_dwordx2 v[208:209], v[198:199], off offset:128
	v_pk_add_f32 v[190:191], v[48:49], v[128:129]
	v_pk_add_f32 v[192:193], v[50:51], v[130:131]
	v_pk_add_f32 v[194:195], v[44:45], v[124:125]
	v_pk_add_f32 v[196:197], v[46:47], v[126:127]
	v_pk_mul_f32 v[190:191], v[190:191], s[98:99]
	v_pk_mul_f32 v[192:193], v[192:193], s[98:99]
	v_pk_mul_f32 v[194:195], v[194:195], s[98:99]
	v_pk_mul_f32 v[196:197], v[196:197], s[98:99]
	v_exp_f32_e32 v190, v190
	v_exp_f32_e32 v191, v191
	v_exp_f32_e32 v192, v192
	v_exp_f32_e32 v193, v193
	v_exp_f32_e32 v194, v194
	v_exp_f32_e32 v195, v195
	v_exp_f32_e32 v196, v196
	v_exp_f32_e32 v197, v197
	v_pk_add_f32 v[190:191], v[190:191], 1.0 op_sel_hi:[1,0]
	v_pk_add_f32 v[192:193], v[192:193], 1.0 op_sel_hi:[1,0]
	v_pk_add_f32 v[194:195], v[194:195], 1.0 op_sel_hi:[1,0]
	v_pk_add_f32 v[196:197], v[196:197], 1.0 op_sel_hi:[1,0]
	v_rcp_f32_e32 v190, v190
	v_rcp_f32_e32 v191, v191
	v_rcp_f32_e32 v192, v192
	v_rcp_f32_e32 v193, v193
	v_rcp_f32_e32 v194, v194
	v_rcp_f32_e32 v195, v195
	v_rcp_f32_e32 v196, v196
	v_rcp_f32_e32 v197, v197
	v_pk_fma_f32 v[190:191], v[190:191], s[2:3], 0.5 op_sel_hi:[1,0,0]
	v_pk_fma_f32 v[192:193], v[192:193], s[2:3], 0.5 op_sel_hi:[1,0,0]
	v_pk_fma_f32 v[194:195], v[194:195], s[2:3], 0.5 op_sel_hi:[1,0,0]
	v_pk_fma_f32 v[196:197], v[196:197], s[2:3], 0.5 op_sel_hi:[1,0,0]
	v_cvt_u32_f32_e32 v190, v190
	v_cvt_u32_f32_e32 v191, v191
	v_cvt_u32_f32_sdwa v192, v192 dst_sel:WORD_1 dst_unused:UNUSED_PAD src0_sel:DWORD
	v_cvt_u32_f32_sdwa v193, v193 dst_sel:BYTE_3 dst_unused:UNUSED_PAD src0_sel:DWORD
	v_cvt_u32_f32_e32 v194, v194
	v_cvt_u32_f32_e32 v195, v195
	v_cvt_u32_f32_sdwa v196, v196 dst_sel:WORD_1 dst_unused:UNUSED_PAD src0_sel:DWORD
	v_cvt_u32_f32_sdwa v197, v197 dst_sel:BYTE_3 dst_unused:UNUSED_PAD src0_sel:DWORD
	s_mov_b64 s[40:41], 0x48000
	v_lshl_add_u64 v[206:207], v[160:161], 0, s[40:41]
	v_lshl_or_b32 v190, v191, 8, v190
; __device__ __forceinline__ float sigmoidf_fast(float x) { return __builtin_amdgcn_rcpf(1.0f + __builtin_amdgcn_exp2f(-1.44269504089f * x)); }
;     __device__ __forceinline__ void operator()(const f32x4 (&acc)[2][2][4][2], const Unit& u, int wr, int wc, int fr, int fq) const {
;     ...
;                 for (int bj = 0; bj < 2; ++bj) { const f32x4 v0 = acc[ai][bj][m][0], v1 = acc[ai][bj][m][1]; unsigned q[8];
; #pragma unroll
;                     for (int j = 0; j < 4; ++j) { q[j] = (unsigned)(255.0f * sigmoidf_fast(v0[j] + b[bj][j]) + 0.5f); q[4 + j] = (unsigned)(255.0f * sigmoidf_fast(v1[j] + b[bj][4 + j]) + 0.5f); }
;                     u32x2 w; w.x = q[0] | (q[1] << 8) | (q[2] << 16) | (q[3] << 24); w.y = q[4] | (q[5] << 8) | (q[6] << 16) | (q[7] << 24);
;                     *(u32x2*)(rowp + bj * HALF) = w; } }
	v_lshl_or_b32 v194, v195, 8, v194
	v_or3_b32 v190, v190, v192, v193
	v_or3_b32 v191, v194, v196, v197
	global_store_dwordx2 v[206:207], v[190:191], off
	v_pk_add_f32 v[198:199], v[40:41], v[112:113]
	v_pk_add_f32 v[200:201], v[42:43], v[114:115]
	v_pk_add_f32 v[202:203], v[36:37], v[108:109]
	v_pk_add_f32 v[204:205], v[38:39], v[110:111]
	v_pk_mul_f32 v[198:199], v[198:199], s[98:99]
	v_pk_mul_f32 v[200:201], v[200:201], s[98:99]
	v_pk_mul_f32 v[202:203], v[202:203], s[98:99]
	v_pk_mul_f32 v[204:205], v[204:205], s[98:99]
	v_exp_f32_e32 v198, v198
	v_exp_f32_e32 v199, v199
	v_exp_f32_e32 v200, v200
	v_exp_f32_e32 v201, v201
	v_exp_f32_e32 v202, v202
	v_exp_f32_e32 v203, v203
	v_exp_f32_e32 v204, v204
	v_exp_f32_e32 v205, v205
	v_pk_add_f32 v[198:199], v[198:199], 1.0 op_sel_hi:[1,0]
	v_pk_add_f32 v[200:201], v[200:201], 1.0 op_sel_hi:[1,0]
	v_pk_add_f32 v[202:203], v[202:203], 1.0 op_sel_hi:[1,0]
	v_pk_add_f32 v[204:205], v[204:205], 1.0 op_sel_hi:[1,0]
	v_rcp_f32_e32 v198, v198
	v_rcp_f32_e32 v199, v199
	v_rcp_f32_e32 v200, v200
	v_rcp_f32_e32 v201, v201
	v_rcp_f32_e32 v202, v202
	v_rcp_f32_e32 v203, v203
	v_rcp_f32_e32 v204, v204
	v_rcp_f32_e32 v205, v205
	v_pk_fma_f32 v[198:199], v[198:199], s[2:3], 0.5 op_sel_hi:[1,0,0]
	v_pk_fma_f32 v[200:201], v[200:201], s[2:3], 0.5 op_sel_hi:[1,0,0]
	v_pk_fma_f32 v[202:203], v[202:203], s[2:3], 0.5 op_sel_hi:[1,0,0]
	v_pk_fma_f32 v[204:205], v[204:205], s[2:3], 0.5 op_sel_hi:[1,0,0]
	v_cvt_u32_f32_e32 v198, v198
	v_cvt_u32_f32_e32 v199, v199
	v_cvt_u32_f32_sdwa v200, v200 dst_sel:WORD_1 dst_unused:UNUSED_PAD src0_sel:DWORD
	v_cvt_u32_f32_sdwa v201, v201 dst_sel:BYTE_3 dst_unused:UNUSED_PAD src0_sel:DWORD
	v_cvt_u32_f32_e32 v202, v202
	v_cvt_u32_f32_e32 v203, v203
	v_cvt_u32_f32_sdwa v204, v204 dst_sel:WORD_1 dst_unused:UNUSED_PAD src0_sel:DWORD
	v_cvt_u32_f32_sdwa v205, v205 dst_sel:BYTE_3 dst_unused:UNUSED_PAD src0_sel:DWORD
	v_lshl_or_b32 v198, v199, 8, v198
	v_lshl_or_b32 v202, v203, 8, v202
	v_or3_b32 v198, v198, v200, v201
	v_or3_b32 v199, v202, v204, v205
	global_store_dwordx2 v[206:207], v[198:199], off offset:128
	v_pk_add_f32 v[190:191], v[30:31], v[128:129]
	v_pk_add_f32 v[192:193], v[32:33], v[130:131]
	v_pk_add_f32 v[194:195], v[26:27], v[124:125]
	v_pk_add_f32 v[196:197], v[28:29], v[126:127]
	v_pk_mul_f32 v[190:191], v[190:191], s[98:99]
	v_pk_mul_f32 v[192:193], v[192:193], s[98:99]
	v_pk_mul_f32 v[194:195], v[194:195], s[98:99]
	v_pk_mul_f32 v[196:197], v[196:197], s[98:99]
	v_exp_f32_e32 v190, v190
	v_exp_f32_e32 v191, v191
	v_exp_f32_e32 v192, v192
	v_exp_f32_e32 v193, v193
	v_exp_f32_e32 v194, v194
	v_exp_f32_e32 v195, v195
	v_exp_f32_e32 v196, v196
	v_exp_f32_e32 v197, v197
	v_pk_add_f32 v[190:191], v[190:191], 1.0 op_sel_hi:[1,0]
	v_pk_add_f32 v[192:193], v[192:193], 1.0 op_sel_hi:[1,0]
	v_pk_add_f32 v[194:195], v[194:195], 1.0 op_sel_hi:[1,0]
	v_pk_add_f32 v[196:197], v[196:197], 1.0 op_sel_hi:[1,0]
	v_rcp_f32_e32 v190, v190
	v_rcp_f32_e32 v191, v191
	v_rcp_f32_e32 v192, v192
	v_rcp_f32_e32 v193, v193
	v_rcp_f32_e32 v194, v194
	v_rcp_f32_e32 v195, v195
	v_rcp_f32_e32 v196, v196
	v_rcp_f32_e32 v197, v197
	v_pk_fma_f32 v[190:191], v[190:191], s[2:3], 0.5 op_sel_hi:[1,0,0]
	v_pk_fma_f32 v[192:193], v[192:193], s[2:3], 0.5 op_sel_hi:[1,0,0]
	v_pk_fma_f32 v[194:195], v[194:195], s[2:3], 0.5 op_sel_hi:[1,0,0]
	v_pk_fma_f32 v[196:197], v[196:197], s[2:3], 0.5 op_sel_hi:[1,0,0]
	v_cvt_u32_f32_e32 v190, v190
	v_cvt_u32_f32_e32 v191, v191
	v_cvt_u32_f32_sdwa v192, v192 dst_sel:WORD_1 dst_unused:UNUSED_PAD src0_sel:DWORD
	v_cvt_u32_f32_sdwa v193, v193 dst_sel:BYTE_3 dst_unused:UNUSED_PAD src0_sel:DWORD
	v_cvt_u32_f32_e32 v194, v194
	v_cvt_u32_f32_e32 v195, v195
	v_cvt_u32_f32_sdwa v196, v196 dst_sel:WORD_1 dst_unused:UNUSED_PAD src0_sel:DWORD
	v_cvt_u32_f32_sdwa v197, v197 dst_sel:BYTE_3 dst_unused:UNUSED_PAD src0_sel:DWORD
	s_mov_b64 s[40:41], 0x50000
	v_lshl_add_u64 v[208:209], v[160:161], 0, s[40:41]
	v_lshl_or_b32 v190, v191, 8, v190
	v_lshl_or_b32 v194, v195, 8, v194
	v_or3_b32 v190, v190, v192, v193
	v_or3_b32 v191, v194, v196, v197
	global_store_dwordx2 v[208:209], v[190:191], off
	v_pk_add_f32 v[198:199], v[22:23], v[112:113]
	v_pk_add_f32 v[200:201], v[24:25], v[114:115]
	v_pk_add_f32 v[202:203], v[18:19], v[108:109]
	v_pk_add_f32 v[204:205], v[20:21], v[110:111]
	v_pk_mul_f32 v[198:199], v[198:199], s[98:99]
	v_pk_mul_f32 v[200:201], v[200:201], s[98:99]
	v_pk_mul_f32 v[202:203], v[202:203], s[98:99]
	v_pk_mul_f32 v[204:205], v[204:205], s[98:99]
	v_exp_f32_e32 v198, v198
	v_exp_f32_e32 v199, v199
	v_exp_f32_e32 v200, v200
	v_exp_f32_e32 v201, v201
	v_exp_f32_e32 v202, v202
	v_exp_f32_e32 v203, v203
	v_exp_f32_e32 v204, v204
	v_exp_f32_e32 v205, v205
	v_pk_add_f32 v[198:199], v[198:199], 1.0 op_sel_hi:[1,0]
	v_pk_add_f32 v[200:201], v[200:201], 1.0 op_sel_hi:[1,0]
	v_pk_add_f32 v[202:203], v[202:203], 1.0 op_sel_hi:[1,0]
	v_pk_add_f32 v[204:205], v[204:205], 1.0 op_sel_hi:[1,0]
	v_rcp_f32_e32 v198, v198
	v_rcp_f32_e32 v199, v199
	v_rcp_f32_e32 v200, v200
	v_rcp_f32_e32 v201, v201
	v_rcp_f32_e32 v202, v202
	v_rcp_f32_e32 v203, v203
; __device__ __forceinline__ float sigmoidf_fast(float x) { return __builtin_amdgcn_rcpf(1.0f + __builtin_amdgcn_exp2f(-1.44269504089f * x)); }
; #define PG8_BAR __builtin_amdgcn_s_barrier()
;     __device__ __forceinline__ void operator()(const f32x4 (&acc)[2][2][4][2], const Unit& u, int wr, int wc, int fr, int fq) const {
;     ...
;                 for (int bj = 0; bj < 2; ++bj) { const f32x4 v0 = acc[ai][bj][m][0], v1 = acc[ai][bj][m][1]; unsigned q[8];
; #pragma unroll
;                     for (int j = 0; j < 4; ++j) { q[j] = (unsigned)(255.0f * sigmoidf_fast(v0[j] + b[bj][j]) + 0.5f); q[4 + j] = (unsigned)(255.0f * sigmoidf_fast(v1[j] + b[bj][4 + j]) + 0.5f); }
;                     u32x2 w; w.x = q[0] | (q[1] << 8) | (q[2] << 16) | (q[3] << 24); w.y = q[4] | (q[5] << 8) | (q[6] << 16) | (q[7] << 24);
;                     *(u32x2*)(rowp + bj * HALF) = w; } }
;     ...
;         if (!has_next) break;
;         if (!Epi::SEGMENTED || cur.seg == 2)
; #pragma unroll
;         for (int a = 0; a < 2; ++a)
; #pragma unroll
;             for (int b = 0; b < 2; ++b)
; #pragma unroll
;                 for (int m = 0; m < 4; ++m)
; #pragma unroll
;                     for (int n = 0; n < 2; ++n) acc[a][b][m][n] = (f32x4){0.f, 0.f, 0.f, 0.f};
;         cur = nxt; cA = nA; cB = nB; ++ui;
;         if constexpr (ALIGN_EPI) { if (wr == 1) PG8_BAR; }
	v_rcp_f32_e32 v204, v204
	v_rcp_f32_e32 v205, v205
	v_pk_fma_f32 v[198:199], v[198:199], s[2:3], 0.5 op_sel_hi:[1,0,0]
	v_pk_fma_f32 v[200:201], v[200:201], s[2:3], 0.5 op_sel_hi:[1,0,0]
	v_pk_fma_f32 v[202:203], v[202:203], s[2:3], 0.5 op_sel_hi:[1,0,0]
	v_pk_fma_f32 v[204:205], v[204:205], s[2:3], 0.5 op_sel_hi:[1,0,0]
	v_cvt_u32_f32_e32 v198, v198
	v_cvt_u32_f32_e32 v199, v199
	v_cvt_u32_f32_sdwa v200, v200 dst_sel:WORD_1 dst_unused:UNUSED_PAD src0_sel:DWORD
	v_cvt_u32_f32_sdwa v201, v201 dst_sel:BYTE_3 dst_unused:UNUSED_PAD src0_sel:DWORD
	v_cvt_u32_f32_e32 v202, v202
	v_cvt_u32_f32_e32 v203, v203
	v_cvt_u32_f32_sdwa v204, v204 dst_sel:WORD_1 dst_unused:UNUSED_PAD src0_sel:DWORD
	v_cvt_u32_f32_sdwa v205, v205 dst_sel:BYTE_3 dst_unused:UNUSED_PAD src0_sel:DWORD
	v_lshl_or_b32 v198, v199, 8, v198
	v_lshl_or_b32 v202, v203, 8, v202
	v_or3_b32 v198, v198, v200, v201
	v_or3_b32 v199, v202, v204, v205
	global_store_dwordx2 v[208:209], v[198:199], off offset:128
	v_pk_add_f32 v[190:191], v[14:15], v[128:129]
	v_pk_add_f32 v[192:193], v[16:17], v[130:131]
	v_pk_add_f32 v[194:195], v[10:11], v[124:125]
	v_pk_add_f32 v[196:197], v[12:13], v[126:127]
	v_pk_mul_f32 v[190:191], v[190:191], s[98:99]
	v_pk_mul_f32 v[192:193], v[192:193], s[98:99]
	v_pk_mul_f32 v[194:195], v[194:195], s[98:99]
	v_pk_mul_f32 v[196:197], v[196:197], s[98:99]
	v_exp_f32_e32 v190, v190
	v_exp_f32_e32 v191, v191
	v_exp_f32_e32 v192, v192
	v_exp_f32_e32 v193, v193
	v_exp_f32_e32 v194, v194
	v_exp_f32_e32 v195, v195
	v_exp_f32_e32 v196, v196
	v_exp_f32_e32 v197, v197
	v_pk_add_f32 v[190:191], v[190:191], 1.0 op_sel_hi:[1,0]
	v_pk_add_f32 v[192:193], v[192:193], 1.0 op_sel_hi:[1,0]
	v_pk_add_f32 v[194:195], v[194:195], 1.0 op_sel_hi:[1,0]
	v_pk_add_f32 v[196:197], v[196:197], 1.0 op_sel_hi:[1,0]
	v_rcp_f32_e32 v190, v190
	v_rcp_f32_e32 v191, v191
	v_rcp_f32_e32 v192, v192
	v_rcp_f32_e32 v193, v193
	v_rcp_f32_e32 v194, v194
	v_rcp_f32_e32 v195, v195
	v_rcp_f32_e32 v196, v196
	v_rcp_f32_e32 v197, v197
	v_pk_fma_f32 v[190:191], v[190:191], s[2:3], 0.5 op_sel_hi:[1,0,0]
	v_pk_fma_f32 v[192:193], v[192:193], s[2:3], 0.5 op_sel_hi:[1,0,0]
	v_pk_fma_f32 v[194:195], v[194:195], s[2:3], 0.5 op_sel_hi:[1,0,0]
	v_pk_fma_f32 v[196:197], v[196:197], s[2:3], 0.5 op_sel_hi:[1,0,0]
	v_cvt_u32_f32_e32 v190, v190
	v_cvt_u32_f32_e32 v191, v191
	v_cvt_u32_f32_sdwa v192, v192 dst_sel:WORD_1 dst_unused:UNUSED_PAD src0_sel:DWORD
	v_cvt_u32_f32_sdwa v193, v193 dst_sel:BYTE_3 dst_unused:UNUSED_PAD src0_sel:DWORD
	v_cvt_u32_f32_e32 v194, v194
	v_cvt_u32_f32_e32 v195, v195
	v_cvt_u32_f32_sdwa v196, v196 dst_sel:WORD_1 dst_unused:UNUSED_PAD src0_sel:DWORD
	v_cvt_u32_f32_sdwa v197, v197 dst_sel:BYTE_3 dst_unused:UNUSED_PAD src0_sel:DWORD
	s_mov_b64 s[40:41], 0x58000
	v_lshl_add_u64 v[206:207], v[160:161], 0, s[40:41]
	v_lshl_or_b32 v190, v191, 8, v190
	v_lshl_or_b32 v194, v195, 8, v194
	v_or3_b32 v190, v190, v192, v193
	v_or3_b32 v191, v194, v196, v197
	global_store_dwordx2 v[206:207], v[190:191], off
	v_pk_add_f32 v[198:199], v[6:7], v[112:113]
	v_pk_add_f32 v[200:201], v[8:9], v[114:115]
	v_pk_add_f32 v[202:203], v[2:3], v[108:109]
	v_pk_add_f32 v[204:205], v[4:5], v[110:111]
	v_pk_mul_f32 v[198:199], v[198:199], s[98:99]
	v_pk_mul_f32 v[200:201], v[200:201], s[98:99]
	v_pk_mul_f32 v[202:203], v[202:203], s[98:99]
	v_pk_mul_f32 v[204:205], v[204:205], s[98:99]
	v_exp_f32_e32 v198, v198
	v_exp_f32_e32 v199, v199
	v_exp_f32_e32 v200, v200
	v_exp_f32_e32 v201, v201
	v_exp_f32_e32 v202, v202
	v_exp_f32_e32 v203, v203
	v_exp_f32_e32 v204, v204
	v_exp_f32_e32 v205, v205
	v_pk_add_f32 v[198:199], v[198:199], 1.0 op_sel_hi:[1,0]
	v_pk_add_f32 v[200:201], v[200:201], 1.0 op_sel_hi:[1,0]
	v_pk_add_f32 v[202:203], v[202:203], 1.0 op_sel_hi:[1,0]
	v_pk_add_f32 v[204:205], v[204:205], 1.0 op_sel_hi:[1,0]
	v_rcp_f32_e32 v198, v198
	v_rcp_f32_e32 v199, v199
	v_rcp_f32_e32 v200, v200
	v_rcp_f32_e32 v201, v201
	v_rcp_f32_e32 v202, v202
	v_rcp_f32_e32 v203, v203
	v_rcp_f32_e32 v204, v204
	v_rcp_f32_e32 v205, v205
	v_pk_fma_f32 v[198:199], v[198:199], s[2:3], 0.5 op_sel_hi:[1,0,0]
	v_pk_fma_f32 v[200:201], v[200:201], s[2:3], 0.5 op_sel_hi:[1,0,0]
	v_pk_fma_f32 v[202:203], v[202:203], s[2:3], 0.5 op_sel_hi:[1,0,0]
	v_pk_fma_f32 v[204:205], v[204:205], s[2:3], 0.5 op_sel_hi:[1,0,0]
	v_cvt_u32_f32_e32 v198, v198
	v_cvt_u32_f32_e32 v199, v199
	v_cvt_u32_f32_sdwa v200, v200 dst_sel:WORD_1 dst_unused:UNUSED_PAD src0_sel:DWORD
	v_cvt_u32_f32_sdwa v201, v201 dst_sel:BYTE_3 dst_unused:UNUSED_PAD src0_sel:DWORD
	v_cvt_u32_f32_e32 v202, v202
	v_cvt_u32_f32_e32 v203, v203
	v_cvt_u32_f32_sdwa v204, v204 dst_sel:WORD_1 dst_unused:UNUSED_PAD src0_sel:DWORD
	v_cvt_u32_f32_sdwa v205, v205 dst_sel:BYTE_3 dst_unused:UNUSED_PAD src0_sel:DWORD
	v_lshl_or_b32 v198, v199, 8, v198
	v_lshl_or_b32 v202, v203, 8, v202
	v_or3_b32 v198, v198, v200, v201
	v_or3_b32 v199, v202, v204, v205
	s_and_b64 vcc, exec, s[38:39]
	s_mov_b64 s[38:39], -1
	global_store_dwordx2 v[206:207], v[198:199], off offset:128
	s_cbranch_vccnz .LBB0_1492
	s_andn2_b64 vcc, exec, s[36:37]
	s_cbranch_vccnz .LBB0_1491
	s_barrier
	s_branch .LBB0_1491

; __device__ __forceinline__ unsigned cvt_pk_bf16(float lo, float hi) { f32x2c v = {lo, hi}; bf16x2c b = __builtin_convertvector(v, bf16x2c); return __builtin_bit_cast(unsigned, b); }
; __device__ __forceinline__ float ub0(unsigned w) { return (float)(w & 0xFFu); }
; __device__ __forceinline__ float ub1(unsigned w) { return (float)((w >> 8) & 0xFFu); }
; __device__ __forceinline__ float ub3(unsigned w) { return (float)(w >> 24); }
;     __device__ __forceinline__ void operator()(f32x4 (&acc)[2][2][4][2], const Unit& u, int wr, int wc, int fr, int fq) const {
;         const int row0 = u.pm * BM + wr * 64 + fr, col0 = u.pn * BM + wc * 32 + 8 * fq; const int sg = u.seg; const bool fin = sg == 2;
;         const unsigned char* qn = Q + (size_t)row0 * 6144 + sg * 2048 + col0; const unsigned char* qd = fin ? qn : qn + 2048;
;         u32x2 gn[2][4][2], gd[2][4][2];
;     ...
;         BR_LOAD(0); BR_LOAD(1);
; #pragma unroll
;         for (int ai = 0; ai < 2; ++ai) {
; #pragma unroll
;             for (int m = 0; m < 4; ++m)
; #pragma unroll
;                 for (int bj = 0; bj < 2; ++bj) { const u32x2 a = gn[ai][m][bj], d = gd[ai][m][bj];
;                     const float an[8] = {ub0(a.x), ub1(a.x), ub2(a.x), ub3(a.x), ub0(a.y), ub1(a.y), ub2(a.y), ub3(a.y)};
;                     const float dn[8] = {ub0(d.x), ub1(d.x), ub2(d.x), ub3(d.x), ub0(d.y), ub1(d.y), ub2(d.y), ub3(d.y)};
;                     float f[8];
; #pragma unroll
;                     for (int k = 0; k < 8; ++k) { const float rd = __builtin_amdgcn_rcpf(dn[k]); f[k] = an[k] * (fin ? (1.0f / 255.0f) : rd); }
;                     f32x4 v0 = acc[ai][bj][m][0], v1 = acc[ai][bj][m][1];
;                     v0[0] *= f[0]; v0[1] *= f[1]; v0[2] *= f[2]; v0[3] *= f[3]; v1[0] *= f[4]; v1[1] *= f[5]; v1[2] *= f[6]; v1[3] *= f[7];
;                     acc[ai][bj][m][0] = v0; acc[ai][bj][m][1] = v1;
;                     if (fin) { u32x4 w; w.x = cvt_pk_bf16(v0[0], v0[1]); w.y = cvt_pk_bf16(v0[2], v0[3]); w.z = cvt_pk_bf16(v1[0], v1[1]); w.w = cvt_pk_bf16(v1[2], v1[3]);
;                         *(u32x4*)(MO + (size_t)(row0 + ai * HALF + m * 16) * ld + col0 + bj * HALF) = w; } }
;     ...
;         if constexpr (ALIGN_EPI) { if (wr == 0) PG8_BAR; }
;         if constexpr (Q8 == 1) asm volatile("s_nop 15\n\ts_nop 15" ::: "memory");
;         if constexpr (!Epi::AFTER_DRAIN) { E(acc, cur, wr, wc, fr, fq); S.done(cur); }
.LBB0_2026:
	s_lshl_b32 s34, s6, 11
	s_ashr_i32 s35, s34, 31
	v_lshl_add_u32 v144, s42, 8, v234
	s_cmp_eq_u32 s6, 2
	v_mov_b64_e32 v[146:147], s[26:27]
	v_lshl_or_b32 v142, s52, 8, v236
	s_cselect_b64 s[40:41], -1, 0
	v_mad_i64_i32 v[146:147], s[42:43], v144, s33, v[146:147]
	s_and_b64 s[42:43], s[40:41], exec
	v_lshl_add_u64 v[146:147], v[146:147], 0, s[34:35]
	v_ashrrev_i32_e32 v143, 31, v142
	s_cselect_b32 s24, 0, 0x800
	s_cmp_lg_u32 s6, 2
	v_lshl_add_u64 v[146:147], v[146:147], 0, v[142:143]
	s_mov_b32 s6, 0x18000
	v_add_co_u32_e32 v150, vcc, s6, v146
	v_lshl_add_u64 v[148:149], v[146:147], 0, s[24:25]
	s_nop 0
	v_addc_co_u32_e32 v151, vcc, 0, v147, vcc
	v_add_co_u32_e32 v152, vcc, s6, v148
	s_mov_b32 s6, 0x30000
	s_nop 0
	v_addc_co_u32_e32 v153, vcc, 0, v149, vcc
	global_load_dwordx2 v[238:239], v[146:147], off
	global_load_dwordx2 v[240:241], v[148:149], off
	global_load_dwordx2 v[226:227], v[146:147], off offset:128
	global_load_dwordx2 v[224:225], v[148:149], off offset:128
	global_load_dwordx2 v[220:221], v[150:151], off
	global_load_dwordx2 v[222:223], v[152:153], off
	global_load_dwordx2 v[218:219], v[150:151], off offset:128
	global_load_dwordx2 v[216:217], v[152:153], off offset:128
	v_add_co_u32_e32 v150, vcc, s6, v146
	v_ashrrev_i32_e32 v145, 31, v144
	s_nop 0
	v_addc_co_u32_e32 v151, vcc, 0, v147, vcc
	v_add_co_u32_e32 v152, vcc, s6, v148
	s_mov_b32 s6, 0x48000
	s_nop 0
	v_addc_co_u32_e32 v153, vcc, 0, v149, vcc
	global_load_dwordx2 v[212:213], v[150:151], off
	global_load_dwordx2 v[214:215], v[152:153], off
	global_load_dwordx2 v[210:211], v[150:151], off offset:128
	global_load_dwordx2 v[208:209], v[152:153], off offset:128
	v_add_co_u32_e32 v150, vcc, s6, v146
	v_addc_co_u32_e32 v151, vcc, 0, v147, vcc
	v_add_co_u32_e32 v152, vcc, s6, v148
	s_mov_b32 s6, 0xc0000
	s_nop 0
	v_addc_co_u32_e32 v153, vcc, 0, v149, vcc
	global_load_dwordx2 v[204:205], v[150:151], off
	global_load_dwordx2 v[206:207], v[152:153], off
	global_load_dwordx2 v[202:203], v[150:151], off offset:128
	global_load_dwordx2 v[200:201], v[152:153], off offset:128
	v_add_co_u32_e32 v150, vcc, s6, v146
	s_nop 0
	v_addc_co_u32_e32 v151, vcc, 0, v147, vcc
	v_add_co_u32_e32 v152, vcc, s6, v148
	s_mov_b32 s6, 0xd8000
	s_nop 0
	v_addc_co_u32_e32 v153, vcc, 0, v149, vcc
	global_load_dwordx2 v[196:197], v[150:151], off
	global_load_dwordx2 v[198:199], v[152:153], off
	global_load_dwordx2 v[194:195], v[150:151], off offset:128
	global_load_dwordx2 v[192:193], v[152:153], off offset:128
	v_add_co_u32_e32 v150, vcc, s6, v146
	s_nop 0
	v_addc_co_u32_e32 v151, vcc, 0, v147, vcc
	v_add_co_u32_e32 v152, vcc, s6, v148
	s_mov_b32 s6, 0xf0000
	s_nop 0
	v_addc_co_u32_e32 v153, vcc, 0, v149, vcc
	global_load_dwordx2 v[188:189], v[150:151], off
	global_load_dwordx2 v[190:191], v[152:153], off
	global_load_dwordx2 v[186:187], v[150:151], off offset:128
	global_load_dwordx2 v[162:163], v[152:153], off offset:128
	v_add_co_u32_e32 v150, vcc, s6, v146
	s_nop 0
	v_addc_co_u32_e32 v151, vcc, 0, v147, vcc
	v_add_co_u32_e32 v152, vcc, s6, v148
	s_mov_b32 s6, 0x108000
	s_nop 0
	v_addc_co_u32_e32 v153, vcc, 0, v149, vcc
	v_add_co_u32_e32 v146, vcc, s6, v146
	global_load_dwordx2 v[158:159], v[150:151], off
	s_nop 0
	v_addc_co_u32_e32 v147, vcc, 0, v147, vcc
	v_add_co_u32_e32 v242, vcc, s6, v148
	global_load_dwordx2 v[160:161], v[152:153], off
	global_load_dwordx2 v[156:157], v[150:151], off offset:128
	global_load_dwordx2 v[154:155], v[152:153], off offset:128
	v_addc_co_u32_e32 v243, vcc, 0, v149, vcc
	global_load_dwordx2 v[150:151], v[146:147], off
	global_load_dwordx2 v[152:153], v[242:243], off
	global_load_dwordx2 v[148:149], v[146:147], off offset:128
	s_nop 0
	global_load_dwordx2 v[146:147], v[242:243], off offset:128
	s_mov_b64 vcc, s[30:31]
	s_cbranch_vccz .Lm7_nobar
	s_barrier
.Lm7_nobar:
	s_waitcnt vmcnt(30)
	v_cvt_f32_ubyte2_e32 v244, v238
	v_cvt_f32_ubyte0_e32 v248, v240
	v_cvt_f32_ubyte1_e32 v249, v240
	v_cvt_f32_ubyte2_e32 v250, v240
	v_cvt_f32_ubyte3_e32 v240, v240
	v_rcp_iflag_f32_e32 v240, v240
	v_cvt_f32_ubyte0_e32 v242, v238
	v_cvt_f32_ubyte1_e32 v243, v238
	v_cvt_f32_ubyte3_e32 v238, v238
	v_cvt_f32_ubyte0_e32 v251, v241
	v_cndmask_b32_e64 v240, v240, v233, s[40:41]
	v_rcp_iflag_f32_e32 v248, v248
	v_mul_f32_e32 v238, v240, v238
	v_rcp_iflag_f32_e32 v240, v251
	v_cvt_f32_ubyte0_e32 v245, v239
	v_cvt_f32_ubyte1_e32 v252, v241
	v_cndmask_b32_e64 v248, v248, v233, s[40:41]
	v_cndmask_b32_e64 v240, v240, v233, s[40:41]
	v_mul_f32_e32 v242, v248, v242
	v_rcp_iflag_f32_e32 v248, v249
	v_mul_f32_e32 v240, v240, v245
	v_rcp_iflag_f32_e32 v245, v252
	v_cvt_f32_ubyte1_e32 v246, v239
	v_cvt_f32_ubyte2_e32 v253, v241
	v_cvt_f32_ubyte3_e32 v241, v241
	v_cndmask_b32_e64 v248, v248, v233, s[40:41]
	v_cndmask_b32_e64 v245, v245, v233, s[40:41]
	v_mul_f32_e32 v243, v248, v243
	v_rcp_iflag_f32_e32 v248, v250
	v_mul_f32_e32 v245, v245, v246
	v_rcp_iflag_f32_e32 v246, v253
	v_rcp_iflag_f32_e32 v241, v241
	v_cvt_f32_ubyte2_e32 v247, v239
	v_cvt_f32_ubyte3_e32 v239, v239
	v_cndmask_b32_e64 v248, v248, v233, s[40:41]
	v_cndmask_b32_e64 v246, v246, v233, s[40:41]
	v_cndmask_b32_e64 v241, v241, v233, s[40:41]
	v_mul_f32_e32 v244, v248, v244
	v_mul_f32_e32 v246, v246, v247
	v_mul_f32_e32 v239, v241, v239
	v_mul_f32_e32 v128, v128, v242
	v_mul_f32_e32 v129, v129, v243
	v_mul_f32_e32 v130, v130, v244
	v_mul_f32_e32 v131, v131, v238
	v_mul_f32_e32 v124, v124, v240
	v_mul_f32_e32 v125, v125, v245
	v_mul_f32_e32 v126, v126, v246
	v_mul_f32_e32 v127, v127, v239
	s_cbranch_scc1 .LBB0_2028
	v_lshlrev_b64 v[242:243], 12, v[144:145]
	v_lshl_add_u64 v[242:243], s[28:29], 0, v[242:243]
	v_cvt_pk_bf16_f32 v238, v128, v129
	v_cvt_pk_bf16_f32 v239, v130, v131
	v_cvt_pk_bf16_f32 v240, v124, v125
	v_cvt_pk_bf16_f32 v241, v126, v127
	v_lshl_add_u64 v[242:243], v[142:143], 1, v[242:243]
	global_store_dwordx4 v[242:243], v[238:241], off sc0 sc1
